# QK projection: row-tile scan also skipped in closed form under the placement flag
# baseline (speedup 1.0000x reference)
; template <bool WANT_PN> __device__ __forceinline__ int unit_tile(int M, int N, int G, int c, int i) {
;     const int nM = M / 256, nN = N / 256, nwg = nM * nN; const long L = (long)i * G + c; if (L >= nwg) return -1;
;     int wgid = (int)L; { const int q = nwg / pg8::NXCD, r = nwg % pg8::NXCD, xcd = wgid % pg8::NXCD, off = wgid / pg8::NXCD; wgid = (xcd < r ? xcd * (q + 1) : r * (q + 1) + (xcd - r) * q) + off; }
;     const int nig = pg8::WGM * nN, gid = wgid / nig, fm = gid * pg8::WGM, gsz = (nM - fm) < pg8::WGM ? (nM - fm) : pg8::WGM;
;     return WANT_PN ? (wgid % nig) / gsz : fm + ((wgid % nig) % gsz);
.LBB0_1162:
	v_readlane_b32 s101, v249, 48
	s_nop 3
	s_cmp_lg_u32 s101, 0
	s_cselect_b32 s101, 4, 0
	v_writelane_b32 v249, s101, 49
	s_cmp_lt_i32 s30, 13
	s_cselect_b64 s[4:5], -1, 0
	s_and_b64 s[10:11], s[4:5], s[0:1]
	s_andn2_b64 vcc, exec, s[10:11]
	s_cbranch_vccnz .LBB0_1453
	s_ashr_i32 s3, s2, 31
	s_ashr_i32 s33, s22, 31
	s_mov_b32 s64, s22
	s_mov_b32 s65, -1
	s_mov_b32 s4, 16
	s_waitcnt lgkmcnt(0)
	v_mov_b64_e32 v[0:1], 0x3ff
	s_mov_b64 s[0:1], s[2:3]
	s_mov_b32 s67, -1
	s_mov_b32 s66, -1
	s_mov_b32 s8, -1
	v_readlane_b32 s101, v249, 48
	s_nop 3
	s_cmp_eq_u32 s101, 0
	s_cbranch_scc1 .LBB0_1166
	s_and_b32 s65, s2, 7
	s_lshl_b32 s65, s65, 4
	s_bfe_u32 s101, s2, 0x30003
	s_or_b32 s65, s65, s101
	s_add_i32 s67, s65, 8
	s_branch .LBB0_1173
